# gate|up GEMM epilogue: per-row rsqrt factors cached in spare LDS per wave and reused while the workgroup's consecutive tiles stay on the same row panel (skips 8 loads + 16 bpermutes + 8 rsq per reused
# speedup vs baseline: 1.0218x; 1.0218x over previous
.LBB0_131:
	s_mov_b32 s52, -1
	v_writelane_b32 v248, s52, 41
	s_lshl_b32 s36, s11, 6
	v_mov_b32_e32 v9, v199
	v_readlane_b32 s1, v251, 0
	s_cmp_ge_i32 s1, s36
	v_readfirstlane_b32 s19, v9
	s_mov_b32 s55, s44
	s_cbranch_scc1 .LBB0_151
	v_lshlrev_b32_e32 v0, 4, v9
	s_waitcnt lgkmcnt(0)
	v_add_u32_e32 v1, 0x2000, v0
	v_ashrrev_i32_e32 v2, 31, v1
	v_lshrrev_b32_e32 v2, 22, v2
	v_add_u32_e32 v2, v1, v2
	v_ashrrev_i32_e32 v8, 10, v2
	v_mul_i32_i24_e32 v2, 0x400, v8
	v_sub_u32_e32 v1, v1, v2
	v_lshrrev_b32_e32 v2, 4, v1
	v_bitop3_b32 v1, v2, v1, 32 bitop3:0x6c
	v_ashrrev_i32_e32 v2, 31, v1
	v_lshrrev_b32_e32 v2, 26, v2
	v_add_u32_e32 v2, v1, v2
	v_lshlrev_b32_e32 v3, 3, v8
	v_ashrrev_i32_e32 v10, 6, v2
	v_and_b32_e32 v3, -16, v3
	v_add_u32_e32 v3, v10, v3
	v_and_b32_e32 v4, 3, v10
	s_mov_b32 s2, 0x1fffe0
	v_lshrrev_b32_e32 v5, 2, v3
	v_lshlrev_b32_e32 v6, 1, v3
	v_and_b32_e32 v2, 0xc0, v2
	v_and_or_b32 v4, v3, s2, v4
	v_and_b32_e32 v5, 4, v5
	v_and_b32_e32 v6, 24, v6
	v_sub_u32_e32 v1, v1, v2
	v_or3_b32 v4, v4, v5, v6
	v_lshlrev_b32_e32 v5, 5, v8
	v_ashrrev_i16_sdwa v1, v223, sext(v1) dst_sel:DWORD dst_unused:UNUSED_PAD src0_sel:DWORD src1_sel:BYTE_0
	v_and_b32_e32 v5, 32, v5
	v_bfe_i32 v11, v1, 0, 16
	v_add_lshl_u32 v1, v5, v11, 1
	s_waitcnt vmcnt(0)
	v_lshl_add_u32 v152, v4, 11, v1
	v_lshl_add_u32 v154, v3, 11, v1
	v_bfe_i32 v1, v9, 27, 1
	v_lshrrev_b32_e32 v1, 22, v1
	v_add_u32_e32 v1, v0, v1
	v_and_b32_e32 v1, 0xfffffc00, v1
	v_sub_u32_e32 v0, v0, v1
	v_lshrrev_b32_e32 v1, 4, v0
	v_ashrrev_i32_e32 v2, 31, v9
	v_bitop3_b32 v0, v1, v0, 32 bitop3:0x6c
	v_lshrrev_b32_e32 v2, 26, v2
	v_ashrrev_i32_e32 v1, 31, v0
	v_add_u32_e32 v2, v9, v2
	v_lshrrev_b32_e32 v1, 26, v1
	v_ashrrev_i32_e32 v13, 6, v2
	v_add_u32_e32 v1, v0, v1
	v_lshlrev_b32_e32 v2, 3, v13
	v_ashrrev_i32_e32 v12, 6, v1
	v_and_b32_e32 v2, -16, v2
	v_add_u32_e32 v2, v12, v2
	v_and_b32_e32 v3, 3, v12
	s_ashr_i32 s21, s19, 6
	v_and_or_b32 v3, v2, s2, v3
	s_lshl_b32 s2, s11, 3
	v_readlane_b32 s12, v250, 5
	s_ashr_i32 s20, s19, 8
	s_lshl_b32 s1, s21, 10
	s_or_b32 s3, s2, 1
	v_readlane_b32 s13, v250, 6
	s_and_b64 s[12:13], s[12:13], exec
	v_and_b32_e32 v1, 0xc0, v1
	s_cselect_b32 s12, s3, s2
	s_lshl_b32 s9, s11, 2
	v_sub_u32_e32 v0, v0, v1
	v_cvt_f32_u32_e32 v1, s9
	v_lshrrev_b32_e32 v4, 2, v2
	v_lshlrev_b32_e32 v5, 1, v2
	v_and_b32_e32 v4, 4, v4
	v_and_b32_e32 v5, 24, v5
	v_rcp_iflag_f32_e32 v1, v1
	v_or3_b32 v3, v3, v4, v5
	v_lshlrev_b32_e32 v4, 5, v13
	v_ashrrev_i16_sdwa v0, v223, sext(v0) dst_sel:DWORD dst_unused:UNUSED_PAD src0_sel:DWORD src1_sel:BYTE_0
	v_and_b32_e32 v4, 32, v4
	v_bfe_i32 v14, v0, 0, 16
	v_add_lshl_u32 v0, v4, v14, 1
	v_lshl_add_u32 v196, v3, 11, v0
	v_lshl_add_u32 v156, v2, 11, v0
	v_mul_f32_e32 v0, 0x4f7ffffe, v1
	v_cvt_u32_f32_e32 v0, v0
	v_readlane_b32 s11, v250, 12
	s_mul_i32 s11, s12, s11
	v_readlane_b32 s12, v250, 7
	s_add_i32 s12, s11, s12
	s_sub_i32 s11, 0, s9
	v_readfirstlane_b32 s15, v0
	s_mul_i32 s11, s11, s15
	s_mul_hi_u32 s11, s15, s11
	s_abs_i32 s14, s12
	s_add_i32 s11, s15, s11
	s_mul_hi_u32 s15, s14, s11
	s_mul_i32 s17, s15, s9
	s_sub_i32 s14, s14, s17
	s_ashr_i32 s13, s12, 31
	s_add_i32 s17, s15, 1
	s_sub_i32 s18, s14, s9
	s_cmp_ge_u32 s14, s9
	s_cselect_b32 s15, s17, s15
	s_cselect_b32 s14, s18, s14
	s_add_i32 s17, s15, 1
	s_cmp_ge_u32 s14, s9
	s_cselect_b32 s14, s17, s15
	s_xor_b32 s14, s14, s13
	s_sub_i32 s13, s14, s13
	s_lshl_b32 s14, s13, 2
	s_sub_i32 s15, 64, s14
	s_min_i32 s15, s15, 4
	s_sext_i32_i16 s17, s15
	v_cvt_f32_i32_e32 v0, s17
	s_mul_i32 s13, s13, s9
	s_sub_i32 s22, s12, s13
	s_sext_i32_i16 s12, s22
	v_cvt_f32_i32_e32 v1, s12
	v_rcp_iflag_f32_e32 v2, v0
	s_xor_b32 s12, s12, s17
	s_ashr_i32 s12, s12, 30
	s_or_b32 s17, s12, 1
	v_mul_f32_e32 v2, v1, v2
	v_trunc_f32_e32 v2, v2
	v_fma_f32 v1, -v2, v0, v1
	v_cvt_i32_f32_e32 v2, v2
	v_cmp_ge_f32_e64 s[12:13], |v1|, |v0|
	s_and_b64 s[12:13], s[12:13], exec
	s_cselect_b32 s12, s17, 0
	v_readfirstlane_b32 s13, v2
	s_add_i32 s18, s13, s12
	s_mul_i32 s12, s18, s15
	s_sub_i32 s12, s22, s12
	s_sext_i32_i16 s12, s12
	s_add_i32 s34, s14, s12
	s_ashr_i32 s35, s34, 31
	s_bfe_i64 s[14:15], s[18:19], 0x100000
	s_lshl_b64 s[12:13], s[34:35], 19
	s_lshl_b64 s[14:15], s[14:15], 19
	s_add_u32 s44, s6, s14
	s_addc_u32 s45, s7, s15
	s_add_i32 s14, s1, 0
	s_add_i32 m0, s14, 0x10000
	v_mov_b32_e32 v153, v197
	global_load_lds_dwordx4 v196, s[44:45]
	s_add_i32 m0, s14, 0x12000
	s_add_u32 s22, s44, 0x40000
	global_load_lds_dwordx4 v152, s[44:45]
	s_addc_u32 s23, s45, 0
	s_add_i32 m0, s14, 0x14000
	v_mov_b32_e32 v157, v197
	global_load_lds_dwordx4 v196, s[22:23]
	s_add_i32 m0, s14, 0x16000
	s_add_u32 s40, s80, s12
	s_addc_u32 s41, s81, s13
	s_add_i32 s15, s14, 0x2000
	global_load_lds_dwordx4 v152, s[22:23]
	s_mov_b32 m0, s14
	s_add_u32 s12, s40, 0x40000
	global_load_lds_dwordx4 v156, s[40:41]
	s_mov_b32 m0, s15
	s_addc_u32 s13, s41, 0
	s_add_i32 s17, s14, 0x4000
	global_load_lds_dwordx4 v154, s[40:41]
	s_mov_b32 m0, s17
	s_add_i32 s26, s14, 0x6000
	global_load_lds_dwordx4 v156, s[12:13]
	s_mov_b32 m0, s26
	v_mov_b32_e32 v155, v197
	global_load_lds_dwordx4 v154, s[12:13]
	s_cmp_eq_u32 s20, 1
	s_mov_b32 s56, s30
	v_lshl_add_u64 v[6:7], s[44:45], 0, v[196:197]
	v_lshl_add_u64 v[4:5], s[44:45], 0, v[152:153]
	v_lshl_add_u64 v[0:1], s[40:41], 0, v[156:157]
	s_cselect_b64 s[12:13], -1, 0
	s_cmp_lg_u32 s20, 1
	v_lshl_add_u64 v[2:3], s[40:41], 0, v[154:155]
	s_cbranch_scc1 .LBB0_134
	s_barrier

.LBB0_143:
	s_mov_b32 s53, s34
	v_readlane_b32 s40, v249, 54
	v_readlane_b32 s41, v249, 55
	v_readlane_b32 s52, v248, 41
	s_cmp_lg_u64 s[40:41], 0
	s_cbranch_scc1 .Lepc_miss
	s_cmp_eq_u32 s52, s34
	s_cbranch_scc1 .Lepc_hit
.Lepc_miss:
	v_lshl_add_u32 v180, s34, 8, v184
	v_ashrrev_i32_e32 v181, 31, v180
	v_lshlrev_b64 v[128:129], 6, v[180:181]
	v_or_b32_e32 v178, 16, v180
	v_lshl_add_u64 v[128:129], v[158:159], 0, v[128:129]
	v_ashrrev_i32_e32 v179, 31, v178
	global_load_dwordx4 v[188:191], v[128:129], off
	v_lshlrev_b64 v[128:129], 6, v[178:179]
	v_lshl_add_u64 v[128:129], v[158:159], 0, v[128:129]
	global_load_dwordx4 v[192:195], v[128:129], off
	v_or_b32_e32 v176, 32, v180
	v_ashrrev_i32_e32 v177, 31, v176
	v_lshlrev_b64 v[128:129], 6, v[176:177]
	v_or_b32_e32 v174, 48, v180
	v_lshl_add_u64 v[128:129], v[158:159], 0, v[128:129]
	v_ashrrev_i32_e32 v175, 31, v174
	global_load_dwordx4 v[148:151], v[128:129], off
	v_lshlrev_b64 v[128:129], 6, v[174:175]
	v_lshl_add_u64 v[128:129], v[158:159], 0, v[128:129]
	global_load_dwordx4 v[144:147], v[128:129], off
	v_add_u32_e32 v172, 0x80, v180
	v_ashrrev_i32_e32 v173, 31, v172
	v_lshlrev_b64 v[128:129], 6, v[172:173]
	v_add_u32_e32 v170, 0x90, v180
	v_lshl_add_u64 v[128:129], v[158:159], 0, v[128:129]
	v_ashrrev_i32_e32 v171, 31, v170
	global_load_dwordx4 v[140:143], v[128:129], off
	v_lshlrev_b64 v[128:129], 6, v[170:171]
	v_lshl_add_u64 v[128:129], v[158:159], 0, v[128:129]
	global_load_dwordx4 v[136:139], v[128:129], off
	v_add_u32_e32 v168, 0xa0, v180
	v_ashrrev_i32_e32 v169, 31, v168
	v_lshlrev_b64 v[128:129], 6, v[168:169]
	v_add_u32_e32 v166, 0xb0, v180
	v_lshl_add_u64 v[128:129], v[158:159], 0, v[128:129]
	v_ashrrev_i32_e32 v167, 31, v166
	global_load_dwordx4 v[132:135], v[128:129], off
	v_lshlrev_b64 v[128:129], 6, v[166:167]
	v_lshl_add_u64 v[128:129], v[158:159], 0, v[128:129]
	global_load_dwordx4 v[128:131], v[128:129], off
	v_and_b32_e32 v169, 64, v222
	v_xor_b32_e32 v167, 16, v222
	v_add_u32_e32 v169, 64, v169
	v_cmp_lt_i32_e32 vcc, v167, v169
	s_mov_b32 s34, 0x358637bd
	v_readlane_b32 s40, v249, 54
	v_cndmask_b32_e32 v167, v222, v167, vcc
	v_lshlrev_b32_e32 v173, 2, v167
	v_xor_b32_e32 v167, 32, v222
	v_cmp_lt_i32_e32 vcc, v167, v169
	v_readlane_b32 s41, v249, 55
	v_readlane_b32 s50, v250, 58
	v_cndmask_b32_e32 v167, v222, v167, vcc
	v_lshlrev_b32_e32 v171, 2, v167
	v_pk_mul_f32 v[124:125], v[120:121], v[124:125]
	v_pk_mul_f32 v[116:117], v[112:113], v[116:117]
	v_pk_mul_f32 v[108:109], v[104:105], v[108:109]
	v_pk_mul_f32 v[100:101], v[96:97], v[100:101]
	v_pk_mul_f32 v[92:93], v[88:89], v[92:93]
	v_pk_mul_f32 v[84:85], v[80:81], v[84:85]
	v_pk_mul_f32 v[76:77], v[72:73], v[76:77]
	v_pk_mul_f32 v[68:69], v[64:65], v[68:69]
	v_pk_mul_f32 v[60:61], v[56:57], v[60:61]
	v_pk_mul_f32 v[52:53], v[48:49], v[52:53]
	v_pk_mul_f32 v[44:45], v[40:41], v[44:45]
	v_pk_mul_f32 v[36:37], v[32:33], v[36:37]
	v_pk_mul_f32 v[28:29], v[24:25], v[28:29]
	v_pk_mul_f32 v[20:21], v[16:17], v[20:21]
	v_pk_mul_f32 v[12:13], v[8:9], v[12:13]
	v_pk_mul_f32 v[4:5], v[0:1], v[4:5]
	v_readlane_b32 s51, v250, 59
	s_waitcnt vmcnt(0)
	v_mov_b32_e32 v182, v189
	v_mov_b32_e32 v183, v190
	v_mov_b32_e32 v189, v191
	v_pk_add_f32 v[182:183], v[182:183], v[188:189]
	v_mov_b32_e32 v188, v193
	v_mov_b32_e32 v189, v194
	v_mov_b32_e32 v193, v195
	v_pk_add_f32 v[188:189], v[188:189], v[192:193]
	v_mov_b32_e32 v191, v182
	v_mov_b32_e32 v190, v188
	v_mov_b32_e32 v182, v189
	v_pk_add_f32 v[182:183], v[190:191], v[182:183]
	ds_bpermute_b32 v189, v173, v183
	ds_bpermute_b32 v188, v173, v182
	s_waitcnt lgkmcnt(0)
	v_pk_add_f32 v[182:183], v[182:183], v[188:189]
	ds_bpermute_b32 v189, v171, v183
	ds_bpermute_b32 v188, v171, v182
	s_waitcnt lgkmcnt(0)
	v_pk_add_f32 v[188:189], v[182:183], v[188:189]
	v_mov_b64_e32 v[182:183], s[34:35]
	s_mov_b32 s34, 0x3a800000
	v_pk_fma_f32 v[188:189], v[188:189], s[34:35], v[182:183] op_sel_hi:[1,0,0]
	s_nop 0
	v_mul_f32_e32 v167, 0x4b800000, v189
	v_cmp_gt_f32_e64 s[44:45], s39, v189
	v_cmp_gt_f32_e32 vcc, s39, v188
	s_nop 0
	v_cndmask_b32_e64 v167, v189, v167, s[44:45]
	v_rsq_f32_e32 v167, v167
	v_mov_b32_e32 v189, v150
	v_mov_b32_e32 v150, v145
	v_mov_b32_e32 v145, v147
	v_mul_f32_e32 v169, 0x45800000, v167
	v_cndmask_b32_e64 v169, v167, v169, s[44:45]
	v_mul_f32_e32 v167, 0x4b800000, v188
	v_cndmask_b32_e32 v167, v188, v167, vcc
	v_mov_b32_e32 v188, v149
	v_mov_b32_e32 v149, v151
	v_mov_b32_e32 v151, v146
	v_pk_add_f32 v[148:149], v[188:189], v[148:149]
	v_pk_add_f32 v[144:145], v[150:151], v[144:145]
	v_mov_b32_e32 v147, v148
	v_mov_b32_e32 v146, v144
	v_mov_b32_e32 v148, v145
	v_pk_add_f32 v[144:145], v[146:147], v[148:149]
	ds_bpermute_b32 v147, v173, v145
	ds_bpermute_b32 v146, v173, v144
	v_mov_b32_e32 v148, v141
	v_mov_b32_e32 v149, v142
	v_mov_b32_e32 v141, v143
	v_mov_b32_e32 v142, v137
	v_mov_b32_e32 v143, v138
	v_mov_b32_e32 v137, v139
	v_pk_add_f32 v[140:141], v[148:149], v[140:141]
	v_pk_add_f32 v[136:137], v[142:143], v[136:137]
	s_waitcnt lgkmcnt(0)
	v_pk_add_f32 v[144:145], v[144:145], v[146:147]
	v_mov_b32_e32 v138, v136
	v_mov_b32_e32 v139, v140
	v_mov_b32_e32 v140, v137
	ds_bpermute_b32 v147, v171, v145
	ds_bpermute_b32 v146, v171, v144
	v_pk_add_f32 v[136:137], v[138:139], v[140:141]
	ds_bpermute_b32 v139, v173, v137
	ds_bpermute_b32 v138, v173, v136
	v_rsq_f32_e32 v167, v167
	s_waitcnt lgkmcnt(2)
	v_pk_add_f32 v[144:145], v[144:145], v[146:147]
	v_mul_f32_e32 v150, v169, v169
	v_pk_fma_f32 v[144:145], v[144:145], s[34:35], v[182:183] op_sel_hi:[1,0,0]
	s_waitcnt lgkmcnt(0)
	v_pk_add_f32 v[136:137], v[136:137], v[138:139]
	v_mul_f32_e32 v146, 0x4b800000, v145
	v_cmp_gt_f32_e64 s[44:45], s39, v145
	ds_bpermute_b32 v139, v171, v137
	ds_bpermute_b32 v138, v171, v136
	v_cndmask_b32_e64 v145, v145, v146, s[44:45]
	v_rsq_f32_e32 v145, v145
	v_mul_f32_e32 v175, 0x45800000, v167
	v_cndmask_b32_e32 v167, v167, v175, vcc
	s_waitcnt lgkmcnt(0)
	v_pk_add_f32 v[136:137], v[136:137], v[138:139]
	v_mul_f32_e32 v146, 0x45800000, v145
	v_pk_fma_f32 v[136:137], v[136:137], s[34:35], v[182:183] op_sel_hi:[1,0,0]
	v_cmp_gt_f32_e32 vcc, s39, v144
	v_cndmask_b32_e64 v147, v145, v146, s[44:45]
	v_mul_f32_e32 v145, 0x4b800000, v144
	v_mul_f32_e32 v138, 0x4b800000, v137
	v_cmp_gt_f32_e64 s[44:45], s39, v137
	v_cndmask_b32_e32 v144, v144, v145, vcc
	v_rsq_f32_e32 v144, v144
	v_cndmask_b32_e64 v137, v137, v138, s[44:45]
	v_rsq_f32_e32 v137, v137
	v_mul_f32_e32 v148, v167, v167
	v_mul_f32_e32 v145, 0x45800000, v144
	v_cndmask_b32_e32 v145, v144, v145, vcc
	v_mul_f32_e32 v138, 0x45800000, v137
	v_cmp_gt_f32_e32 vcc, s39, v136
	v_cndmask_b32_e64 v143, v137, v138, s[44:45]
	v_mul_f32_e32 v137, 0x4b800000, v136
	v_cndmask_b32_e32 v136, v136, v137, vcc
	v_rsq_f32_e32 v136, v136
	v_mul_f32_e32 v146, v147, v147
	v_mul_f32_e32 v144, v145, v145
	v_mul_f32_e32 v142, v143, v143
	v_mul_f32_e32 v137, 0x45800000, v136
	v_cndmask_b32_e32 v141, v136, v137, vcc
	v_mov_b32_e32 v136, v133
	v_mov_b32_e32 v137, v134
	v_mov_b32_e32 v133, v135
	v_mov_b32_e32 v134, v129
	v_mov_b32_e32 v135, v130
	v_mov_b32_e32 v129, v131
	v_pk_add_f32 v[132:133], v[136:137], v[132:133]
	v_pk_add_f32 v[128:129], v[134:135], v[128:129]
	v_mov_b32_e32 v131, v132
	v_mov_b32_e32 v130, v128
	v_mov_b32_e32 v132, v129
	v_pk_add_f32 v[128:129], v[130:131], v[132:133]
	ds_bpermute_b32 v131, v173, v129
	ds_bpermute_b32 v130, v173, v128
	v_lshl_or_b32 v132, s33, 7, v186
	v_ashrrev_i32_e32 v133, 31, v132
	v_lshlrev_b64 v[136:137], 1, v[132:133]
	v_mul_f32_e32 v140, v141, v141
	s_waitcnt lgkmcnt(0)
	v_pk_add_f32 v[128:129], v[128:129], v[130:131]
	ds_bpermute_b32 v131, v171, v129
	ds_bpermute_b32 v130, v171, v128
	s_waitcnt lgkmcnt(0)
	v_pk_add_f32 v[128:129], v[128:129], v[130:131]
	s_nop 0
	v_pk_fma_f32 v[128:129], v[128:129], s[34:35], v[182:183] op_sel_hi:[1,0,0]
	s_mov_b64 s[34:35], -1
	v_mul_f32_e32 v130, 0x4b800000, v129
	v_cmp_gt_f32_e64 s[44:45], s39, v129
	v_cmp_gt_f32_e32 vcc, s39, v128
	s_nop 0
	v_cndmask_b32_e64 v129, v129, v130, s[44:45]
	v_rsq_f32_e32 v129, v129
	s_nop 0
	v_mul_f32_e32 v130, 0x45800000, v129
	v_cndmask_b32_e64 v139, v129, v130, s[44:45]
	v_mul_f32_e32 v129, 0x4b800000, v128
	v_cndmask_b32_e32 v128, v128, v129, vcc
	v_rsq_f32_e32 v128, v128
	v_mul_f32_e32 v138, v139, v139
	v_mul_f32_e32 v129, 0x45800000, v128
	v_cndmask_b32_e32 v135, v128, v129, vcc
	v_lshrrev_b32_e32 v182, 6, v199
	v_and_b32_e32 v183, 15, v199
	v_lshlrev_b32_e32 v182, 9, v182
	v_lshl_add_u32 v183, v183, 2, v182
	v_add_u32_e32 v183, 0x20040, v183
	ds_write_b32 v183, v169
	ds_write_b32 v183, v167 offset:64
	ds_write_b32 v183, v147 offset:128
	ds_write_b32 v183, v145 offset:192
	ds_write_b32 v183, v143 offset:256
	ds_write_b32 v183, v141 offset:320
	ds_write_b32 v183, v139 offset:384
	ds_write_b32 v183, v135 offset:448
	v_writelane_b32 v248, s53, 41
	s_branch .Lepc_join
.Lepc_hit:
	v_lshrrev_b32_e32 v182, 6, v199
	v_and_b32_e32 v183, 15, v199
	v_lshlrev_b32_e32 v182, 9, v182
	v_lshl_add_u32 v183, v183, 2, v182
	v_add_u32_e32 v183, 0x20040, v183
	ds_read_b32 v169, v183
	ds_read_b32 v167, v183 offset:64
	ds_read_b32 v147, v183 offset:128
	ds_read_b32 v145, v183 offset:192
	ds_read_b32 v143, v183 offset:256
	ds_read_b32 v141, v183 offset:320
	ds_read_b32 v139, v183 offset:384
	ds_read_b32 v135, v183 offset:448
	v_lshl_add_u32 v180, s34, 8, v184
	v_or_b32_e32 v178, 16, v180
	v_or_b32_e32 v176, 32, v180
	v_or_b32_e32 v174, 48, v180
	v_add_u32_e32 v172, 0x80, v180
	v_add_u32_e32 v170, 0x90, v180
	v_add_u32_e32 v168, 0xa0, v180
	v_add_u32_e32 v166, 0xb0, v180
	v_readlane_b32 s50, v250, 58
	v_readlane_b32 s51, v250, 59
	v_pk_mul_f32 v[124:125], v[120:121], v[124:125]
	v_pk_mul_f32 v[116:117], v[112:113], v[116:117]
	v_pk_mul_f32 v[108:109], v[104:105], v[108:109]
	v_pk_mul_f32 v[100:101], v[96:97], v[100:101]
	v_pk_mul_f32 v[92:93], v[88:89], v[92:93]
	v_pk_mul_f32 v[84:85], v[80:81], v[84:85]
	v_pk_mul_f32 v[76:77], v[72:73], v[76:77]
	v_pk_mul_f32 v[68:69], v[64:65], v[68:69]
	v_pk_mul_f32 v[60:61], v[56:57], v[60:61]
	v_pk_mul_f32 v[52:53], v[48:49], v[52:53]
	v_pk_mul_f32 v[44:45], v[40:41], v[44:45]
	v_pk_mul_f32 v[36:37], v[32:33], v[36:37]
	v_pk_mul_f32 v[28:29], v[24:25], v[28:29]
	v_pk_mul_f32 v[20:21], v[16:17], v[20:21]
	v_pk_mul_f32 v[12:13], v[8:9], v[12:13]
	v_pk_mul_f32 v[4:5], v[0:1], v[4:5]
	v_lshl_or_b32 v132, s33, 7, v186
	v_ashrrev_i32_e32 v133, 31, v132
	v_lshlrev_b64 v[136:137], 1, v[132:133]
	s_waitcnt vmcnt(0)
	s_waitcnt lgkmcnt(0)
	v_mul_f32_e32 v150, v169, v169
	v_mul_f32_e32 v148, v167, v167
	v_mul_f32_e32 v146, v147, v147
	v_mul_f32_e32 v144, v145, v145
	v_mul_f32_e32 v142, v143, v143
	v_mul_f32_e32 v140, v141, v141
	v_mul_f32_e32 v138, v139, v139
	s_mov_b64 s[34:35], -1
.Lepc_join:
	s_andn2_b64 vcc, exec, s[40:41]
	v_mul_f32_e32 v134, v135, v135
	s_cbranch_vccnz .LBB0_145
	v_pk_mul_f32 v[128:129], v[122:123], v[126:127]
	v_pk_mul_f32 v[130:131], v[124:125], v[150:151] op_sel_hi:[1,0]
	v_pk_mul_f32 v[182:183], v[128:129], v[150:151] op_sel_hi:[1,0]
	v_pk_mul_f32 v[128:129], v[114:115], v[118:119]
	v_pk_mul_f32 v[188:189], v[116:117], v[150:151] op_sel_hi:[1,0]
	v_pk_mul_f32 v[190:191], v[128:129], v[150:151] op_sel_hi:[1,0]
	v_cvt_pk_bf16_f32 v128, v130, v131
	v_cvt_pk_bf16_f32 v129, v182, v183
	v_mad_i64_i32 v[182:183], s[34:35], s8, v180, 0
	v_lshl_add_u64 v[182:183], v[182:183], 1, s[82:83]
	v_lshl_add_u64 v[182:183], v[182:183], 0, v[136:137]
	v_cvt_pk_bf16_f32 v130, v188, v189
	v_cvt_pk_bf16_f32 v131, v190, v191
	global_store_dwordx4 v[182:183], v[128:131], off
	v_pk_mul_f32 v[188:189], v[100:101], v[148:149] op_sel_hi:[1,0]
	s_nop 0
	v_pk_mul_f32 v[128:129], v[106:107], v[110:111]
	v_pk_mul_f32 v[130:131], v[108:109], v[148:149] op_sel_hi:[1,0]
	v_pk_mul_f32 v[182:183], v[128:129], v[148:149] op_sel_hi:[1,0]
	v_pk_mul_f32 v[128:129], v[98:99], v[102:103]
	s_nop 0
	v_pk_mul_f32 v[190:191], v[128:129], v[148:149] op_sel_hi:[1,0]
	v_cvt_pk_bf16_f32 v128, v130, v131
	v_cvt_pk_bf16_f32 v129, v182, v183
	v_mad_i64_i32 v[182:183], s[34:35], s8, v178, 0
	v_lshl_add_u64 v[182:183], v[182:183], 1, s[82:83]
	v_lshl_add_u64 v[182:183], v[182:183], 0, v[136:137]
	v_cvt_pk_bf16_f32 v130, v188, v189
	v_cvt_pk_bf16_f32 v131, v190, v191
	global_store_dwordx4 v[182:183], v[128:131], off
	v_pk_mul_f32 v[188:189], v[84:85], v[146:147] op_sel_hi:[1,0]
	s_nop 0
	v_pk_mul_f32 v[128:129], v[90:91], v[94:95]
	v_pk_mul_f32 v[130:131], v[92:93], v[146:147] op_sel_hi:[1,0]
	v_pk_mul_f32 v[182:183], v[128:129], v[146:147] op_sel_hi:[1,0]
	v_pk_mul_f32 v[128:129], v[82:83], v[86:87]
	s_nop 0
	v_pk_mul_f32 v[190:191], v[128:129], v[146:147] op_sel_hi:[1,0]
	v_cvt_pk_bf16_f32 v128, v130, v131
	v_cvt_pk_bf16_f32 v129, v182, v183
	v_mad_i64_i32 v[182:183], s[34:35], s8, v176, 0
	v_lshl_add_u64 v[182:183], v[182:183], 1, s[82:83]
	v_lshl_add_u64 v[182:183], v[182:183], 0, v[136:137]
	v_cvt_pk_bf16_f32 v130, v188, v189
	v_cvt_pk_bf16_f32 v131, v190, v191
	global_store_dwordx4 v[182:183], v[128:131], off
	v_pk_mul_f32 v[188:189], v[68:69], v[144:145] op_sel_hi:[1,0]
	s_nop 0
	v_pk_mul_f32 v[128:129], v[74:75], v[78:79]
	v_pk_mul_f32 v[130:131], v[76:77], v[144:145] op_sel_hi:[1,0]
	v_pk_mul_f32 v[182:183], v[128:129], v[144:145] op_sel_hi:[1,0]
	v_pk_mul_f32 v[128:129], v[66:67], v[70:71]
	s_nop 0
	v_pk_mul_f32 v[190:191], v[128:129], v[144:145] op_sel_hi:[1,0]
	v_cvt_pk_bf16_f32 v128, v130, v131
	v_cvt_pk_bf16_f32 v129, v182, v183
	v_mad_i64_i32 v[182:183], s[34:35], s8, v174, 0
	v_lshl_add_u64 v[182:183], v[182:183], 1, s[82:83]
	v_lshl_add_u64 v[182:183], v[182:183], 0, v[136:137]
	v_cvt_pk_bf16_f32 v130, v188, v189
	v_cvt_pk_bf16_f32 v131, v190, v191
	global_store_dwordx4 v[182:183], v[128:131], off
	v_pk_mul_f32 v[188:189], v[52:53], v[142:143] op_sel_hi:[1,0]
	s_nop 0
	v_pk_mul_f32 v[128:129], v[58:59], v[62:63]
	v_pk_mul_f32 v[130:131], v[60:61], v[142:143] op_sel_hi:[1,0]
	v_pk_mul_f32 v[182:183], v[128:129], v[142:143] op_sel_hi:[1,0]
	v_pk_mul_f32 v[128:129], v[50:51], v[54:55]
	s_nop 0
	v_pk_mul_f32 v[190:191], v[128:129], v[142:143] op_sel_hi:[1,0]
	v_cvt_pk_bf16_f32 v128, v130, v131
	v_cvt_pk_bf16_f32 v129, v182, v183
	v_mad_i64_i32 v[182:183], s[34:35], s8, v172, 0
	v_lshl_add_u64 v[182:183], v[182:183], 1, s[82:83]
	v_lshl_add_u64 v[182:183], v[182:183], 0, v[136:137]
	v_cvt_pk_bf16_f32 v130, v188, v189
	v_cvt_pk_bf16_f32 v131, v190, v191
	global_store_dwordx4 v[182:183], v[128:131], off
	v_pk_mul_f32 v[188:189], v[36:37], v[140:141] op_sel_hi:[1,0]
	s_nop 0
	v_pk_mul_f32 v[128:129], v[42:43], v[46:47]
	v_pk_mul_f32 v[130:131], v[44:45], v[140:141] op_sel_hi:[1,0]
	v_pk_mul_f32 v[182:183], v[128:129], v[140:141] op_sel_hi:[1,0]
	v_pk_mul_f32 v[128:129], v[34:35], v[38:39]
	s_nop 0
	v_pk_mul_f32 v[190:191], v[128:129], v[140:141] op_sel_hi:[1,0]
	v_cvt_pk_bf16_f32 v128, v130, v131
	v_cvt_pk_bf16_f32 v129, v182, v183
	v_mad_i64_i32 v[182:183], s[34:35], s8, v170, 0
	v_lshl_add_u64 v[182:183], v[182:183], 1, s[82:83]
	v_lshl_add_u64 v[182:183], v[182:183], 0, v[136:137]
	v_cvt_pk_bf16_f32 v130, v188, v189
	v_cvt_pk_bf16_f32 v131, v190, v191
	global_store_dwordx4 v[182:183], v[128:131], off
	v_pk_mul_f32 v[188:189], v[20:21], v[138:139] op_sel_hi:[1,0]
	s_nop 0
	v_pk_mul_f32 v[128:129], v[26:27], v[30:31]
	v_pk_mul_f32 v[130:131], v[28:29], v[138:139] op_sel_hi:[1,0]
	v_pk_mul_f32 v[182:183], v[128:129], v[138:139] op_sel_hi:[1,0]
	v_pk_mul_f32 v[128:129], v[18:19], v[22:23]
	s_nop 0
	v_pk_mul_f32 v[190:191], v[128:129], v[138:139] op_sel_hi:[1,0]
	v_cvt_pk_bf16_f32 v128, v130, v131
	v_cvt_pk_bf16_f32 v129, v182, v183
	v_mad_i64_i32 v[182:183], s[34:35], s8, v168, 0
	v_lshl_add_u64 v[182:183], v[182:183], 1, s[82:83]
	v_lshl_add_u64 v[182:183], v[182:183], 0, v[136:137]
	v_cvt_pk_bf16_f32 v130, v188, v189
	v_cvt_pk_bf16_f32 v131, v190, v191
	global_store_dwordx4 v[182:183], v[128:131], off
	s_mov_b64 s[34:35], 0
	v_pk_mul_f32 v[188:189], v[4:5], v[134:135] op_sel_hi:[1,0]
	v_pk_mul_f32 v[128:129], v[10:11], v[14:15]
	v_pk_mul_f32 v[130:131], v[12:13], v[134:135] op_sel_hi:[1,0]
	v_pk_mul_f32 v[182:183], v[128:129], v[134:135] op_sel_hi:[1,0]
	v_pk_mul_f32 v[128:129], v[2:3], v[6:7]
	s_nop 0
	v_pk_mul_f32 v[190:191], v[128:129], v[134:135] op_sel_hi:[1,0]
	v_cvt_pk_bf16_f32 v128, v130, v131
	v_cvt_pk_bf16_f32 v129, v182, v183
	v_cvt_pk_bf16_f32 v130, v188, v189
	s_nop 0
	v_cvt_pk_bf16_f32 v131, v190, v191
